# combo13 + GEMM tile loops clear the 128 accumulators with 64 v_mov_b64 (was 128 v_mov_b32)
# speedup vs baseline: 1.0069x; 1.0046x over previous
; template <class Epi>
; __device__ __forceinline__ void gemm_phase(LAS unsigned char* lds, const Gemm g, const StaticOrder& S, const Epi& E, const int tid) {
;     ...
;         const bool has_next = S.next(ui + 1, nxt);
;         const char* nA = has_next ? PG8_APTR(nxt) : cA; const char* nB = has_next ? PG8_BPTR(nxt) : cB;
;     ...
;         if (!(Epi::CHAIN && cur.n + 1 < S.NS)) {
; #pragma unroll
;         for (int a = 0; a < 2; ++a)
; #pragma unroll
;             for (int b = 0; b < 2; ++b)
; #pragma unroll
;                 for (int m = 0; m < 4; ++m)
; #pragma unroll
;                     for (int n = 0; n < 2; ++n) acc[a][b][m][n] = (f32x4){0.f, 0.f, 0.f, 0.f};
;         }
.LBB0_160:
	s_ashr_i32 s15, s14, 31
	s_lshl_b64 s[16:17], s[14:15], 20
	s_add_u32 s16, s58, s16
	s_addc_u32 s17, s59, s17
	s_and_b64 s[18:19], s[36:37], exec
	s_cselect_b32 s15, s17, s35
	s_cselect_b32 s53, s16, s34
	s_ashr_i32 s13, s12, 31
	s_lshl_b64 s[18:19], s[12:13], 20
	s_add_u32 s18, s40, s18
	s_addc_u32 s19, s41, s19
	s_and_b64 s[38:39], s[36:37], exec
	s_cselect_b32 s13, s19, s1
	s_cselect_b32 s56, s18, s0
	s_add_u32 s34, s34, 0x80080
	s_addc_u32 s35, s35, 0
	s_add_u32 s57, s0, 0x100
	s_addc_u32 s58, s1, 0
	s_mov_b32 s59, -2
	v_mov_b64_e32 v[0:1], 0
	v_mov_b64_e32 v[2:3], 0
	v_mov_b64_e32 v[4:5], 0
	v_mov_b64_e32 v[6:7], 0
	v_mov_b64_e32 v[8:9], 0
	v_mov_b64_e32 v[10:11], 0
	v_mov_b64_e32 v[12:13], 0
	v_mov_b64_e32 v[14:15], 0
	v_mov_b64_e32 v[16:17], 0
	v_mov_b64_e32 v[18:19], 0
	v_mov_b64_e32 v[20:21], 0
	v_mov_b64_e32 v[22:23], 0
	v_mov_b64_e32 v[24:25], 0
	v_mov_b64_e32 v[26:27], 0
	v_mov_b64_e32 v[28:29], 0
	v_mov_b64_e32 v[30:31], 0
	v_mov_b64_e32 v[32:33], 0
	v_mov_b64_e32 v[34:35], 0
	v_mov_b64_e32 v[36:37], 0
	v_mov_b64_e32 v[38:39], 0
	v_mov_b64_e32 v[40:41], 0
	v_mov_b64_e32 v[42:43], 0
	v_mov_b64_e32 v[44:45], 0
	v_mov_b64_e32 v[46:47], 0
	v_mov_b64_e32 v[48:49], 0
	v_mov_b64_e32 v[50:51], 0
	v_mov_b64_e32 v[52:53], 0
	v_mov_b64_e32 v[54:55], 0
	v_mov_b64_e32 v[56:57], 0
	v_mov_b64_e32 v[58:59], 0
	v_mov_b64_e32 v[60:61], 0
	v_mov_b64_e32 v[62:63], 0
	v_mov_b64_e32 v[64:65], 0
	v_mov_b64_e32 v[66:67], 0
	v_mov_b64_e32 v[68:69], 0
	v_mov_b64_e32 v[70:71], 0
	v_mov_b64_e32 v[72:73], 0
	v_mov_b64_e32 v[74:75], 0
	v_mov_b64_e32 v[76:77], 0
	v_mov_b64_e32 v[78:79], 0
	v_mov_b64_e32 v[80:81], 0
	v_mov_b64_e32 v[82:83], 0
	v_mov_b64_e32 v[84:85], 0
	v_mov_b64_e32 v[86:87], 0
	v_mov_b64_e32 v[88:89], 0
	v_mov_b64_e32 v[90:91], 0
	v_mov_b64_e32 v[92:93], 0
	v_mov_b64_e32 v[94:95], 0
	v_mov_b64_e32 v[96:97], 0
	v_mov_b64_e32 v[98:99], 0
	v_mov_b64_e32 v[100:101], 0
	v_mov_b64_e32 v[102:103], 0
	v_mov_b64_e32 v[104:105], 0
	v_mov_b64_e32 v[106:107], 0
	v_mov_b64_e32 v[108:109], 0
	v_mov_b64_e32 v[110:111], 0
	v_mov_b64_e32 v[112:113], 0
	v_mov_b64_e32 v[114:115], 0
	v_mov_b64_e32 v[116:117], 0
	v_mov_b64_e32 v[118:119], 0
	v_mov_b64_e32 v[120:121], 0
	v_mov_b64_e32 v[122:123], 0
	v_mov_b64_e32 v[124:125], 0
	v_mov_b64_e32 v[126:127], 0
	s_cmp_lg_u64 s[10:11], 0
	s_cbranch_scc0 .Lgprio_a
	s_setprio 1

; template <class Epi>
; __device__ __forceinline__ void gemm_phase(LAS unsigned char* lds, const Gemm g, const StaticOrder& S, const Epi& E, const int tid) {
;     ...
;         if (!(Epi::CHAIN && cur.n + 1 < S.NS)) {
; #pragma unroll
;         for (int a = 0; a < 2; ++a)
; #pragma unroll
;             for (int b = 0; b < 2; ++b)
; #pragma unroll
;                 for (int m = 0; m < 4; ++m)
; #pragma unroll
;                     for (int n = 0; n < 2; ++n) acc[a][b][m][n] = (f32x4){0.f, 0.f, 0.f, 0.f};
;         }
.LBB0_232:
	s_add_u32 s42, s0, 0x100
	s_addc_u32 s43, s1, 0
	s_mov_b32 s69, -2
	v_mov_b64_e32 v[0:1], 0
	v_mov_b64_e32 v[2:3], 0
	v_mov_b64_e32 v[4:5], 0
	v_mov_b64_e32 v[6:7], 0
	v_mov_b64_e32 v[8:9], 0
	v_mov_b64_e32 v[10:11], 0
	v_mov_b64_e32 v[12:13], 0
	v_mov_b64_e32 v[14:15], 0
	v_mov_b64_e32 v[16:17], 0
	v_mov_b64_e32 v[18:19], 0
	v_mov_b64_e32 v[20:21], 0
	v_mov_b64_e32 v[22:23], 0
	v_mov_b64_e32 v[24:25], 0
	v_mov_b64_e32 v[26:27], 0
	v_mov_b64_e32 v[28:29], 0
	v_mov_b64_e32 v[30:31], 0
	v_mov_b64_e32 v[32:33], 0
	v_mov_b64_e32 v[34:35], 0
	v_mov_b64_e32 v[36:37], 0
	v_mov_b64_e32 v[38:39], 0
	v_mov_b64_e32 v[40:41], 0
	v_mov_b64_e32 v[42:43], 0
	v_mov_b64_e32 v[44:45], 0
	v_mov_b64_e32 v[46:47], 0
	v_mov_b64_e32 v[48:49], 0
	v_mov_b64_e32 v[50:51], 0
	v_mov_b64_e32 v[52:53], 0
	v_mov_b64_e32 v[54:55], 0
	v_mov_b64_e32 v[56:57], 0
	v_mov_b64_e32 v[58:59], 0
	v_mov_b64_e32 v[60:61], 0
	v_mov_b64_e32 v[62:63], 0
	v_mov_b64_e32 v[64:65], 0
	v_mov_b64_e32 v[66:67], 0
	v_mov_b64_e32 v[68:69], 0
	v_mov_b64_e32 v[70:71], 0
	v_mov_b64_e32 v[72:73], 0
	v_mov_b64_e32 v[74:75], 0
	v_mov_b64_e32 v[76:77], 0
	v_mov_b64_e32 v[78:79], 0
	v_mov_b64_e32 v[80:81], 0
	v_mov_b64_e32 v[82:83], 0
	v_mov_b64_e32 v[84:85], 0
	v_mov_b64_e32 v[86:87], 0
	v_mov_b64_e32 v[88:89], 0
	v_mov_b64_e32 v[90:91], 0
	v_mov_b64_e32 v[92:93], 0
	v_mov_b64_e32 v[94:95], 0
	v_mov_b64_e32 v[96:97], 0
	v_mov_b64_e32 v[98:99], 0
	v_mov_b64_e32 v[100:101], 0
	v_mov_b64_e32 v[102:103], 0
	v_mov_b64_e32 v[104:105], 0
	v_mov_b64_e32 v[106:107], 0
	v_mov_b64_e32 v[108:109], 0
	v_mov_b64_e32 v[110:111], 0
	v_mov_b64_e32 v[112:113], 0
	v_mov_b64_e32 v[114:115], 0
	v_mov_b64_e32 v[116:117], 0
	v_mov_b64_e32 v[118:119], 0
	v_mov_b64_e32 v[120:121], 0
	v_mov_b64_e32 v[122:123], 0
	v_mov_b64_e32 v[124:125], 0
	v_mov_b64_e32 v[126:127], 0
	s_cmp_lg_u64 s[10:11], 0
	s_cbranch_scc0 .Lgprio_b
	s_setprio 1

; template <class Epi>
; __device__ __forceinline__ void gemm_phase(LAS unsigned char* lds, const Gemm g, const StaticOrder& S, const Epi& E, const int tid) {
;     ...
;         const bool has_next = S.next(ui + 1, nxt);
;         const char* nA = has_next ? PG8_APTR(nxt) : cA; const char* nB = has_next ? PG8_BPTR(nxt) : cB;
;     ...
;         if (!(Epi::CHAIN && cur.n + 1 < S.NS)) {
; #pragma unroll
;         for (int a = 0; a < 2; ++a)
; #pragma unroll
;             for (int b = 0; b < 2; ++b)
; #pragma unroll
;                 for (int m = 0; m < 4; ++m)
; #pragma unroll
;                     for (int n = 0; n < 2; ++n) acc[a][b][m][n] = (f32x4){0.f, 0.f, 0.f, 0.f};
;         }
.LBB0_353:
	s_ashr_i32 s49, s48, 31
	s_lshl_b64 s[10:11], s[48:49], 20
	s_add_u32 s52, s38, s10
	s_addc_u32 s53, s39, s11
	s_and_b64 s[10:11], s[40:41], exec
	s_cselect_b32 s10, s53, s1
	s_cselect_b32 s11, s52, s0
	s_ashr_i32 s47, s46, 31
	s_lshl_b64 s[12:13], s[46:47], 20
	v_readlane_b32 s16, v255, 32
	s_add_u32 s12, s16, s12
	v_readlane_b32 s16, v255, 33
	s_addc_u32 s13, s16, s13
	s_and_b64 s[36:37], s[40:41], exec
	s_cselect_b32 s47, s13, s43
	s_cselect_b32 s49, s12, s42
	s_add_u32 s36, s0, 0x80080
	s_addc_u32 s37, s1, 0
	s_add_u32 s69, s42, 0x100
	s_addc_u32 vcc_lo, s43, 0
	s_mov_b32 vcc_hi, -2
	v_mov_b64_e32 v[0:1], 0
	v_mov_b64_e32 v[2:3], 0
	v_mov_b64_e32 v[4:5], 0
	v_mov_b64_e32 v[6:7], 0
	v_mov_b64_e32 v[8:9], 0
	v_mov_b64_e32 v[10:11], 0
	v_mov_b64_e32 v[12:13], 0
	v_mov_b64_e32 v[14:15], 0
	v_mov_b64_e32 v[16:17], 0
	v_mov_b64_e32 v[18:19], 0
	v_mov_b64_e32 v[20:21], 0
	v_mov_b64_e32 v[22:23], 0
	v_mov_b64_e32 v[24:25], 0
	v_mov_b64_e32 v[26:27], 0
	v_mov_b64_e32 v[28:29], 0
	v_mov_b64_e32 v[30:31], 0
	v_mov_b64_e32 v[32:33], 0
	v_mov_b64_e32 v[34:35], 0
	v_mov_b64_e32 v[36:37], 0
	v_mov_b64_e32 v[38:39], 0
	v_mov_b64_e32 v[40:41], 0
	v_mov_b64_e32 v[42:43], 0
	v_mov_b64_e32 v[44:45], 0
	v_mov_b64_e32 v[46:47], 0
	v_mov_b64_e32 v[48:49], 0
	v_mov_b64_e32 v[50:51], 0
	v_mov_b64_e32 v[52:53], 0
	v_mov_b64_e32 v[54:55], 0
	v_mov_b64_e32 v[56:57], 0
	v_mov_b64_e32 v[58:59], 0
	v_mov_b64_e32 v[60:61], 0
	v_mov_b64_e32 v[62:63], 0
	v_mov_b64_e32 v[64:65], 0
	v_mov_b64_e32 v[66:67], 0
	v_mov_b64_e32 v[68:69], 0
	v_mov_b64_e32 v[70:71], 0
	v_mov_b64_e32 v[72:73], 0
	v_mov_b64_e32 v[74:75], 0
	v_mov_b64_e32 v[76:77], 0
	v_mov_b64_e32 v[78:79], 0
	v_mov_b64_e32 v[80:81], 0
	v_mov_b64_e32 v[82:83], 0
	v_mov_b64_e32 v[84:85], 0
	v_mov_b64_e32 v[86:87], 0
	v_mov_b64_e32 v[88:89], 0
	v_mov_b64_e32 v[90:91], 0
	v_mov_b64_e32 v[92:93], 0
	v_mov_b64_e32 v[94:95], 0
	v_mov_b64_e32 v[96:97], 0
	v_mov_b64_e32 v[98:99], 0
	v_mov_b64_e32 v[100:101], 0
	v_mov_b64_e32 v[102:103], 0
	v_mov_b64_e32 v[104:105], 0
	v_mov_b64_e32 v[106:107], 0
	v_mov_b64_e32 v[108:109], 0
	v_mov_b64_e32 v[110:111], 0
	v_mov_b64_e32 v[112:113], 0
	v_mov_b64_e32 v[114:115], 0
	v_mov_b64_e32 v[116:117], 0
	v_mov_b64_e32 v[118:119], 0
	v_mov_b64_e32 v[120:121], 0
	v_mov_b64_e32 v[122:123], 0
	v_mov_b64_e32 v[124:125], 0
	v_mov_b64_e32 v[126:127], 0
	s_cmp_lg_u64 s[34:35], 0
	s_cbranch_scc0 .Lgprio_c
	s_setprio 1

; #define PG8_STAGE(bufoff, gbase, voff) do { _Pragma("unroll") for (int _i = 0; _i < 2; ++_i) \
;         __builtin_amdgcn_global_load_lds((const unsigned*)((const char*)(gbase) + (voff)[_i]), (LAS unsigned*)(lds + (bufoff) + ldsw + _i * 8192), 16, 0, 0); } while (0)
; #define PG8_WAIT_V(n) asm volatile("s_waitcnt vmcnt(" #n ")" ::: "memory")
; #define PG8_BAR __builtin_amdgcn_s_barrier()
; template <class Epi>
; __device__ __forceinline__ void gemm_phase(LAS unsigned char* lds, const Gemm g, const StaticOrder& S, const Epi& E, const int tid) {
;     ...
;     f32x4 acc[2][2][4][2];
; #pragma unroll
;     for (int a = 0; a < 2; ++a)
; #pragma unroll
;         for (int b = 0; b < 2; ++b)
; #pragma unroll
;             for (int m = 0; m < 4; ++m)
; #pragma unroll
;                 for (int n = 0; n < 2; ++n) acc[a][b][m][n] = (f32x4){0.f, 0.f, 0.f, 0.f};
;     bf16x8 At[4][2], B0[2][2], B1[2][2];
;     const char* cA = PG8_APTR(cur); const char* cB = PG8_BPTR(cur);
;     PG8_STAGE(PG8_SB(0, 0), cB, voffB); PG8_STAGE(PG8_SB(0, 1), cB + hsB, voffB); PG8_STAGE(PG8_SA(0, 0), cA, voffA); PG8_STAGE(PG8_SA(0, 1), cA + hsA, voffA);
;     if (wr == 1) PG8_BAR;
;     PG8_WAIT_V(2); PG8_BAR;
;     PG8_STAGE(PG8_SB(1, 0), cB + kstep, voffB); PG8_STAGE(PG8_SA(1, 0), cA + kstep, voffA); PG8_STAGE(PG8_SB(1, 1), cB + hsB + kstep, voffB);
;     PG8_WAIT_V(6); PG8_BAR;
.LBB0_811:
	v_lshrrev_b32_e32 v17, 1, v214
	v_readlane_b32 s48, v255, 28
	v_and_b32_e32 v17, 24, v17
	v_readlane_b32 s49, v255, 29
	v_and_b32_e32 v16, 15, v214
	v_lshlrev_b32_e32 v18, 1, v17
	v_lshl_add_u64 v[8:9], s[48:49], 0, v[168:169]
	v_mov_b32_e32 v129, v169
	v_readlane_b32 s36, v254, 36
	v_lshl_or_b32 v231, s12, 6, v16
	v_lshl_or_b32 v16, v16, 6, v18
	v_lshlrev_b32_e32 v18, 2, v214
	s_lshl_b32 s1, s1, 5
	v_lshl_add_u64 v[10:11], s[48:49], 0, v[128:129]
	v_mov_b32_e32 v133, v169
	v_readlane_b32 s37, v254, 37
	s_lshl_b32 s12, s12, 13
	v_and_b32_e32 v18, 32, v18
	s_and_b32 s1, s1, 0x60
	s_add_i32 m0, s7, 0x18000
	v_lshl_add_u64 v[8:9], v[8:9], 0, s[28:29]
	v_lshl_add_u64 v[12:13], s[36:37], 0, v[132:133]
	v_mov_b32_e32 v131, v169
	v_bitop3_b32 v19, v16, s12, v18 bitop3:0xde
	s_lshl_b32 s12, s1, 7
	s_waitcnt vmcnt(2)
	s_barrier
	global_load_lds_dwordx4 v[8:9], off
	v_lshl_add_u64 v[8:9], v[10:11], 0, s[28:29]
	s_add_i32 m0, s7, 0x1a000
	s_add_i32 s56, s7, 0x8000
	v_lshl_add_u64 v[14:15], s[36:37], 0, v[130:131]
	v_bitop3_b32 v232, s12, v16, v18 bitop3:0xf6
	global_load_lds_dwordx4 v[8:9], off
	v_lshl_add_u64 v[8:9], v[12:13], 0, s[28:29]
	s_mov_b32 m0, s56
	s_add_i32 s57, s7, 0xa000
	v_readlane_b32 s12, v255, 30
	global_load_lds_dwordx4 v[8:9], off
	v_lshl_add_u64 v[8:9], v[14:15], 0, s[28:29]
	s_mov_b32 m0, s57
	v_readlane_b32 s13, v255, 31
	global_load_lds_dwordx4 v[8:9], off
	s_add_i32 m0, s7, 0x1c000
	v_lshl_add_u64 v[8:9], s[12:13], 0, v[168:169]
	global_load_lds_dwordx4 v[8:9], off
	v_lshl_add_u64 v[8:9], s[12:13], 0, v[128:129]
	s_add_i32 m0, s7, 0x1e000
	s_movk_i32 s15, 0xc00
	global_load_lds_dwordx4 v[8:9], off
	v_lshrrev_b32_e32 v5, 1, v5
	v_mul_lo_u32 v4, v4, s15
	s_mov_b32 s14, 0xc000
	s_cmpk_lt_u32 s0, 0x100
	v_or_b32_e32 v233, s1, v17
	v_mad_u64_u32 v[4:5], s[0:1], v5, s14, v[4:5]
	v_or_b32_e32 v4, v4, v6
	v_add_lshl_u32 v4, v4, v7, 1
	v_mov_b32_e32 v5, v169
	s_mov_b64 s[18:19], 0xc0080
	v_lshl_add_u64 v[134:135], v[4:5], 0, s[18:19]
	v_lshrrev_b32_e32 v4, 1, v0
	v_mul_lo_u32 v0, v1, s15
	v_mad_u64_u32 v[0:1], s[0:1], v4, s14, v[0:1]
	v_or_b32_e32 v0, v0, v2
	s_waitcnt vmcnt(6)
	v_add_lshl_u32 v0, v0, v3, 1
	v_mov_b32_e32 v1, v169
	v_lshl_add_u64 v[136:137], v[0:1], 0, s[18:19]
	s_cselect_b64 s[12:13], -1, 0
	s_mov_b64 s[16:17], 0xc0080
	s_mov_b32 s52, 0
	v_add_u32_e32 v234, 0, v19
	v_readlane_b32 s53, v254, 29
	v_readlane_b32 s60, v254, 33
	s_mov_b32 s58, 0
	v_mov_b64_e32 v[0:1], 0
	v_mov_b64_e32 v[2:3], 0
	v_mov_b64_e32 v[4:5], 0
	v_mov_b64_e32 v[6:7], 0
	v_mov_b64_e32 v[8:9], 0
	v_mov_b64_e32 v[10:11], 0
	v_mov_b64_e32 v[12:13], 0
	v_mov_b64_e32 v[14:15], 0
	v_mov_b64_e32 v[16:17], 0
	v_mov_b64_e32 v[18:19], 0
	v_mov_b64_e32 v[20:21], 0
	v_mov_b64_e32 v[22:23], 0
	v_mov_b64_e32 v[24:25], 0
	v_mov_b64_e32 v[26:27], 0
	v_mov_b64_e32 v[28:29], 0
	v_mov_b64_e32 v[30:31], 0
	v_mov_b64_e32 v[32:33], 0
	v_mov_b64_e32 v[34:35], 0
	v_mov_b64_e32 v[36:37], 0
	v_mov_b64_e32 v[38:39], 0
	v_mov_b64_e32 v[40:41], 0
	v_mov_b64_e32 v[42:43], 0
	v_mov_b64_e32 v[44:45], 0
	v_mov_b64_e32 v[46:47], 0
	v_mov_b64_e32 v[48:49], 0
	v_mov_b64_e32 v[50:51], 0
	v_mov_b64_e32 v[52:53], 0
	v_mov_b64_e32 v[54:55], 0
	v_mov_b64_e32 v[56:57], 0
	v_mov_b64_e32 v[58:59], 0
	v_mov_b64_e32 v[60:61], 0
	v_mov_b64_e32 v[62:63], 0
	v_mov_b64_e32 v[64:65], 0
	v_mov_b64_e32 v[66:67], 0
	v_mov_b64_e32 v[68:69], 0
	v_mov_b64_e32 v[70:71], 0
	v_mov_b64_e32 v[72:73], 0
	v_mov_b64_e32 v[74:75], 0
	v_mov_b64_e32 v[76:77], 0
	v_mov_b64_e32 v[78:79], 0
	v_mov_b64_e32 v[80:81], 0
	v_mov_b64_e32 v[82:83], 0
	v_mov_b64_e32 v[84:85], 0
	v_mov_b64_e32 v[86:87], 0
	v_mov_b64_e32 v[88:89], 0
	v_mov_b64_e32 v[90:91], 0
	v_mov_b64_e32 v[92:93], 0
	v_mov_b64_e32 v[94:95], 0
	v_mov_b64_e32 v[96:97], 0
	v_mov_b64_e32 v[98:99], 0
	v_mov_b64_e32 v[100:101], 0
	v_mov_b64_e32 v[102:103], 0
	v_mov_b64_e32 v[104:105], 0
	v_mov_b64_e32 v[106:107], 0
	v_mov_b64_e32 v[108:109], 0
	v_mov_b64_e32 v[110:111], 0
	v_mov_b64_e32 v[112:113], 0
	v_mov_b64_e32 v[114:115], 0
	v_mov_b64_e32 v[116:117], 0
	v_mov_b64_e32 v[118:119], 0
	v_mov_b64_e32 v[120:121], 0
	v_mov_b64_e32 v[122:123], 0
	v_mov_b64_e32 v[124:125], 0
	v_mov_b64_e32 v[126:127], 0
	s_barrier
	s_branch .LBB0_814

; template <class Epi>
; __device__ __forceinline__ void gemm_phase(LAS unsigned char* lds, const Gemm g, const StaticOrder& S, const Epi& E, const int tid) {
;     ...
;         const bool has_next = S.next(ui + 1, nxt);
;         const char* nA = has_next ? PG8_APTR(nxt) : cA; const char* nB = has_next ? PG8_BPTR(nxt) : cB;
;     ...
;         if (!(Epi::CHAIN && cur.n + 1 < S.NS)) {
; #pragma unroll
;         for (int a = 0; a < 2; ++a)
; #pragma unroll
;             for (int b = 0; b < 2; ++b)
; #pragma unroll
;                 for (int m = 0; m < 4; ++m)
; #pragma unroll
;                     for (int n = 0; n < 2; ++n) acc[a][b][m][n] = (f32x4){0.f, 0.f, 0.f, 0.f};
;         }
.LBB0_1003:
	s_ashr_i32 s13, s12, 31
	s_lshl_b64 s[14:15], s[12:13], 20
	s_add_u32 s14, s58, s14
	s_addc_u32 s15, s59, s15
	s_and_b64 s[16:17], s[38:39], exec
	s_cselect_b32 s13, s15, s19
	s_cselect_b32 s49, s14, s18
	s_ashr_i32 s11, s10, 31
	s_lshl_b64 s[16:17], s[10:11], 20
	s_add_u32 s16, s36, s16
	s_addc_u32 s17, s37, s17
	s_and_b64 s[24:25], s[38:39], exec
	s_cselect_b32 s11, s17, s1
	s_cselect_b32 s52, s16, s0
	s_add_u32 s18, s18, 0x80080
	s_addc_u32 s19, s19, 0
	s_add_u32 s53, s0, 0x100
	s_addc_u32 s56, s1, 0
	s_mov_b32 s57, -2
	v_mov_b64_e32 v[0:1], 0
	v_mov_b64_e32 v[2:3], 0
	v_mov_b64_e32 v[4:5], 0
	v_mov_b64_e32 v[6:7], 0
	v_mov_b64_e32 v[8:9], 0
	v_mov_b64_e32 v[10:11], 0
	v_mov_b64_e32 v[12:13], 0
	v_mov_b64_e32 v[14:15], 0
	v_mov_b64_e32 v[16:17], 0
	v_mov_b64_e32 v[18:19], 0
	v_mov_b64_e32 v[20:21], 0
	v_mov_b64_e32 v[22:23], 0
	v_mov_b64_e32 v[24:25], 0
	v_mov_b64_e32 v[26:27], 0
	v_mov_b64_e32 v[28:29], 0
	v_mov_b64_e32 v[30:31], 0
	v_mov_b64_e32 v[32:33], 0
	v_mov_b64_e32 v[34:35], 0
	v_mov_b64_e32 v[36:37], 0
	v_mov_b64_e32 v[38:39], 0
	v_mov_b64_e32 v[40:41], 0
	v_mov_b64_e32 v[42:43], 0
	v_mov_b64_e32 v[44:45], 0
	v_mov_b64_e32 v[46:47], 0
	v_mov_b64_e32 v[48:49], 0
	v_mov_b64_e32 v[50:51], 0
	v_mov_b64_e32 v[52:53], 0
	v_mov_b64_e32 v[54:55], 0
	v_mov_b64_e32 v[56:57], 0
	v_mov_b64_e32 v[58:59], 0
	v_mov_b64_e32 v[60:61], 0
	v_mov_b64_e32 v[62:63], 0
	v_mov_b64_e32 v[64:65], 0
	v_mov_b64_e32 v[66:67], 0
	v_mov_b64_e32 v[68:69], 0
	v_mov_b64_e32 v[70:71], 0
	v_mov_b64_e32 v[72:73], 0
	v_mov_b64_e32 v[74:75], 0
	v_mov_b64_e32 v[76:77], 0
	v_mov_b64_e32 v[78:79], 0
	v_mov_b64_e32 v[80:81], 0
	v_mov_b64_e32 v[82:83], 0
	v_mov_b64_e32 v[84:85], 0
	v_mov_b64_e32 v[86:87], 0
	v_mov_b64_e32 v[88:89], 0
	v_mov_b64_e32 v[90:91], 0
	v_mov_b64_e32 v[92:93], 0
	v_mov_b64_e32 v[94:95], 0
	v_mov_b64_e32 v[96:97], 0
	v_mov_b64_e32 v[98:99], 0
	v_mov_b64_e32 v[100:101], 0
	v_mov_b64_e32 v[102:103], 0
	v_mov_b64_e32 v[104:105], 0
	v_mov_b64_e32 v[106:107], 0
	v_mov_b64_e32 v[108:109], 0
	v_mov_b64_e32 v[110:111], 0
	v_mov_b64_e32 v[112:113], 0
	v_mov_b64_e32 v[114:115], 0
	v_mov_b64_e32 v[116:117], 0
	v_mov_b64_e32 v[118:119], 0
	v_mov_b64_e32 v[120:121], 0
	v_mov_b64_e32 v[122:123], 0
	v_mov_b64_e32 v[124:125], 0
	v_mov_b64_e32 v[126:127], 0
	s_cmp_lg_u64 s[8:9], 0
	s_cbranch_scc0 .Lgprio_f
	s_setprio 1

; template <class Epi>
; __device__ __forceinline__ void gemm_phase(LAS unsigned char* lds, const Gemm g, const StaticOrder& S, const Epi& E, const int tid) {
;     ...
;         if (!(Epi::CHAIN && cur.n + 1 < S.NS)) {
; #pragma unroll
;         for (int a = 0; a < 2; ++a)
; #pragma unroll
;             for (int b = 0; b < 2; ++b)
; #pragma unroll
;                 for (int m = 0; m < 4; ++m)
; #pragma unroll
;                     for (int n = 0; n < 2; ++n) acc[a][b][m][n] = (f32x4){0.f, 0.f, 0.f, 0.f};
;         }
.LBB0_1075:
	s_add_u32 s38, s0, 0x100
	s_addc_u32 s39, s1, 0
	s_mov_b32 s53, -2
	v_mov_b64_e32 v[0:1], 0
	v_mov_b64_e32 v[2:3], 0
	v_mov_b64_e32 v[4:5], 0
	v_mov_b64_e32 v[6:7], 0
	v_mov_b64_e32 v[8:9], 0
	v_mov_b64_e32 v[10:11], 0
	v_mov_b64_e32 v[12:13], 0
	v_mov_b64_e32 v[14:15], 0
	v_mov_b64_e32 v[16:17], 0
	v_mov_b64_e32 v[18:19], 0
	v_mov_b64_e32 v[20:21], 0
	v_mov_b64_e32 v[22:23], 0
	v_mov_b64_e32 v[24:25], 0
	v_mov_b64_e32 v[26:27], 0
	v_mov_b64_e32 v[28:29], 0
	v_mov_b64_e32 v[30:31], 0
	v_mov_b64_e32 v[32:33], 0
	v_mov_b64_e32 v[34:35], 0
	v_mov_b64_e32 v[36:37], 0
	v_mov_b64_e32 v[38:39], 0
	v_mov_b64_e32 v[40:41], 0
	v_mov_b64_e32 v[42:43], 0
	v_mov_b64_e32 v[44:45], 0
	v_mov_b64_e32 v[46:47], 0
	v_mov_b64_e32 v[48:49], 0
	v_mov_b64_e32 v[50:51], 0
	v_mov_b64_e32 v[52:53], 0
	v_mov_b64_e32 v[54:55], 0
	v_mov_b64_e32 v[56:57], 0
	v_mov_b64_e32 v[58:59], 0
	v_mov_b64_e32 v[60:61], 0
	v_mov_b64_e32 v[62:63], 0
	v_mov_b64_e32 v[64:65], 0
	v_mov_b64_e32 v[66:67], 0
	v_mov_b64_e32 v[68:69], 0
	v_mov_b64_e32 v[70:71], 0
	v_mov_b64_e32 v[72:73], 0
	v_mov_b64_e32 v[74:75], 0
	v_mov_b64_e32 v[76:77], 0
	v_mov_b64_e32 v[78:79], 0
	v_mov_b64_e32 v[80:81], 0
	v_mov_b64_e32 v[82:83], 0
	v_mov_b64_e32 v[84:85], 0
	v_mov_b64_e32 v[86:87], 0
	v_mov_b64_e32 v[88:89], 0
	v_mov_b64_e32 v[90:91], 0
	v_mov_b64_e32 v[92:93], 0
	v_mov_b64_e32 v[94:95], 0
	v_mov_b64_e32 v[96:97], 0
	v_mov_b64_e32 v[98:99], 0
	v_mov_b64_e32 v[100:101], 0
	v_mov_b64_e32 v[102:103], 0
	v_mov_b64_e32 v[104:105], 0
	v_mov_b64_e32 v[106:107], 0
	v_mov_b64_e32 v[108:109], 0
	v_mov_b64_e32 v[110:111], 0
	v_mov_b64_e32 v[112:113], 0
	v_mov_b64_e32 v[114:115], 0
	v_mov_b64_e32 v[116:117], 0
	v_mov_b64_e32 v[118:119], 0
	v_mov_b64_e32 v[120:121], 0
	v_mov_b64_e32 v[122:123], 0
	v_mov_b64_e32 v[124:125], 0
	v_mov_b64_e32 v[126:127], 0
	s_cmp_lg_u64 s[6:7], 0
	s_cbranch_scc0 .Lgprio_g
	s_setprio 1
